# EpiBf16 epilogue: one vmcnt wait after row-sum loads; bf16 results lane-transposed (ds_bpermute) so 4 consecutive lanes store 64 contiguous bytes
# speedup vs baseline: 1.0198x; 1.0198x over previous
.LBB0_773:
	v_mov_b32_e32 v132, v179
	v_mov_b32_e32 v174, v178
	s_mov_b32 s6, s27
	s_mov_b32 s42, s59
	v_mov_b32_e32 v156, 0
	v_lshl_add_u32 v182, s6, 6, v132
	v_lshl_add_u32 v172, s71, 8, v182
	v_mbcnt_lo_u32_b32 v243, -1, 0
	v_mbcnt_hi_u32_b32 v243, -1, v243
	v_and_b32_e32 v242, 3, v243
	v_lshlrev_b32_e32 v242, 6, v242
	v_and_b32_e32 v244, 60, v243
	v_or_b32_e32 v242, v242, v244
	v_lshrrev_b32_e32 v244, 2, v243
	v_lshl_add_u32 v244, s6, 6, v244
	v_lshl_add_u32 v244, s71, 8, v244
	v_add_u32_e32 v245, 0x80, v244
	v_cndmask_b32_e64 v132, 0, 1, s[14:15]
	v_cmp_ne_u32_e64 s[6:7], 1, v132
	s_andn2_b64 vcc, exec, s[14:15]
	v_ashrrev_i32_e32 v173, 31, v172
	v_mov_b32_e32 v160, 0
	v_mov_b32_e32 v161, 0
	v_mov_b32_e32 v162, 0
	v_mov_b32_e32 v163, 0
	s_cbranch_vccnz .LBB0_775
	v_lshl_add_u64 v[132:133], v[172:173], 4, s[40:41]
	global_load_dwordx4 v[160:163], v[132:133], off

.LBB0_789:
	s_lshl_b32 s9, s70, 8
	s_and_b32 s43, s9, 0x300
	s_lshl_b32 s42, s42, 5
	s_and_b64 s[6:7], s[80:81], exec
	s_cselect_b32 s6, s9, s43
	s_add_i32 s42, s42, s6
	s_ashr_i32 s65, s70, 2
	v_ashrrev_i32_e32 v173, 5, v182
	v_lshl_add_u32 v174, v174, 3, s42
	v_cmp_eq_u32_e32 vcc, s65, v173
	v_ashrrev_i32_e32 v175, 31, v174
	v_and_b32_e32 v246, 3, v243
	v_lshl_add_u32 v246, v246, 3, s42
	v_ashrrev_i32_e32 v247, 31, v246
	s_or_b64 s[52:53], s[80:81], vcc
	s_mov_b64 s[42:43], 0
	s_waitcnt vmcnt(0)
	s_and_saveexec_b64 s[6:7], s[52:53]
	s_cbranch_execz .LBB0_795
	v_mov_b32_e32 v184, v161
	v_mov_b32_e32 v185, v162
	v_mov_b32_e32 v161, v163
	v_pk_add_f32 v[160:161], v[184:185], v[160:161]
	v_mad_i64_i32 v[162:163], s[42:43], s26, v244, 0
	v_add_f32_e32 v160, v160, v161
	v_fmamk_f32 v160, v160, 0x3a800000, v241
	v_rsq_f32_e32 v160, v160
	v_lshl_add_u64 v[162:163], v[162:163], 1, s[34:35]
	v_lshl_add_u64 v[162:163], v[246:247], 1, v[162:163]
	s_and_b64 s[42:43], s[80:81], exec
	v_cndmask_b32_e64 v160, v160, 1.0, s[44:45]
	v_mul_f32_e32 v160, s38, v160
	v_pk_mul_f32 v[130:131], v[130:131], v[160:161] op_sel_hi:[1,0]
	v_pk_mul_f32 v[128:129], v[128:129], v[160:161] op_sel_hi:[1,0]
	v_pk_mul_f32 v[184:185], v[126:127], v[160:161] op_sel_hi:[1,0]
	v_pk_mul_f32 v[126:127], v[124:125], v[160:161] op_sel_hi:[1,0]
	v_cvt_pk_bf16_f32 v124, v128, v129
	v_cvt_pk_bf16_f32 v125, v130, v131
	v_pk_mul_f32 v[122:123], v[122:123], v[160:161] op_sel_hi:[1,0]
	v_cvt_pk_bf16_f32 v126, v126, v127
	v_cvt_pk_bf16_f32 v127, v184, v185
	ds_bpermute_b32 v226, v242, v124
	ds_bpermute_b32 v227, v242, v125
	ds_bpermute_b32 v228, v242, v126
	ds_bpermute_b32 v229, v242, v127
	v_pk_mul_f32 v[120:121], v[120:121], v[160:161] op_sel_hi:[1,0]
	s_nop 0
	v_pk_mul_f32 v[124:125], v[118:119], v[160:161] op_sel_hi:[1,0]
	v_pk_mul_f32 v[118:119], v[116:117], v[160:161] op_sel_hi:[1,0]
	v_cvt_pk_bf16_f32 v116, v120, v121
	v_cvt_pk_bf16_f32 v117, v122, v123
	s_nop 0
	v_cvt_pk_bf16_f32 v118, v118, v119
	v_cvt_pk_bf16_f32 v119, v124, v125
	ds_bpermute_b32 v230, v242, v116
	ds_bpermute_b32 v231, v242, v117
	ds_bpermute_b32 v232, v242, v118
	ds_bpermute_b32 v233, v242, v119
	s_waitcnt lgkmcnt(0)
	global_store_dwordx4 v[162:163], v[226:229], off
	global_store_dwordx4 v[162:163], v[230:233], off offset:256
	s_or_b64 exec, exec, s[6:7]
	s_xor_b64 s[52:53], s[42:43], -1
	s_and_saveexec_b64 s[6:7], s[52:53]
	s_cbranch_execnz .LBB0_796

.LBB0_792:
	v_add_f32_e32 v117, v156, v157
	v_add_f32_e32 v118, v158, v159
	v_add_f32_e32 v117, v117, v118
	v_fmamk_f32 v117, v117, 0x3a800000, v241
	v_rsq_f32_e32 v118, v117
	v_add_u32_e32 v116, 16, v244
	v_mad_i64_i32 v[116:117], s[42:43], s26, v116, 0
	v_cndmask_b32_e64 v118, v118, 1.0, s[44:45]
	v_lshl_add_u64 v[116:117], v[116:117], 1, s[34:35]
	v_mul_f32_e32 v118, s38, v118
	v_lshl_add_u64 v[116:117], v[246:247], 1, v[116:117]
	v_pk_mul_f32 v[114:115], v[114:115], v[118:119] op_sel_hi:[1,0]
	v_pk_mul_f32 v[112:113], v[112:113], v[118:119] op_sel_hi:[1,0]
	v_pk_mul_f32 v[120:121], v[110:111], v[118:119] op_sel_hi:[1,0]
	v_pk_mul_f32 v[110:111], v[108:109], v[118:119] op_sel_hi:[1,0]
	v_cvt_pk_bf16_f32 v108, v112, v113
	v_cvt_pk_bf16_f32 v109, v114, v115
	s_and_b64 s[52:53], s[80:81], exec
	v_cvt_pk_bf16_f32 v110, v110, v111
	v_cvt_pk_bf16_f32 v111, v120, v121
	ds_bpermute_b32 v226, v242, v108
	ds_bpermute_b32 v227, v242, v109
	ds_bpermute_b32 v228, v242, v110
	ds_bpermute_b32 v229, v242, v111
	v_pk_mul_f32 v[106:107], v[106:107], v[118:119] op_sel_hi:[1,0]
	v_pk_mul_f32 v[104:105], v[104:105], v[118:119] op_sel_hi:[1,0]
	v_pk_mul_f32 v[108:109], v[102:103], v[118:119] op_sel_hi:[1,0]
	v_pk_mul_f32 v[102:103], v[100:101], v[118:119] op_sel_hi:[1,0]
	v_cvt_pk_bf16_f32 v100, v104, v105
	v_cvt_pk_bf16_f32 v101, v106, v107
	s_nop 0
	v_cvt_pk_bf16_f32 v102, v102, v103
	v_cvt_pk_bf16_f32 v103, v108, v109
	ds_bpermute_b32 v230, v242, v100
	ds_bpermute_b32 v231, v242, v101
	ds_bpermute_b32 v232, v242, v102
	ds_bpermute_b32 v233, v242, v103
	s_waitcnt lgkmcnt(0)
	global_store_dwordx4 v[116:117], v[226:229], off
	global_store_dwordx4 v[116:117], v[230:233], off offset:256
	s_or_b64 exec, exec, s[6:7]
	s_xor_b64 s[42:43], s[52:53], -1
	s_and_saveexec_b64 s[6:7], s[42:43]
	s_cbranch_execnz .LBB0_798

.LBB0_794:
	v_add_f32_e32 v101, v152, v153
	v_add_f32_e32 v102, v154, v155
	v_add_f32_e32 v101, v101, v102
	v_fmamk_f32 v101, v101, 0x3a800000, v241
	v_rsq_f32_e32 v102, v101
	v_add_u32_e32 v100, 32, v244
	v_mad_i64_i32 v[100:101], s[42:43], s26, v100, 0
	v_cndmask_b32_e64 v102, v102, 1.0, s[44:45]
	v_lshl_add_u64 v[100:101], v[100:101], 1, s[34:35]
	v_mul_f32_e32 v102, s38, v102
	v_lshl_add_u64 v[100:101], v[246:247], 1, v[100:101]
	v_pk_mul_f32 v[98:99], v[98:99], v[102:103] op_sel_hi:[1,0]
	v_pk_mul_f32 v[96:97], v[96:97], v[102:103] op_sel_hi:[1,0]
	v_pk_mul_f32 v[104:105], v[94:95], v[102:103] op_sel_hi:[1,0]
	v_pk_mul_f32 v[94:95], v[92:93], v[102:103] op_sel_hi:[1,0]
	v_cvt_pk_bf16_f32 v92, v96, v97
	v_cvt_pk_bf16_f32 v93, v98, v99
	s_and_b64 s[70:71], s[80:81], exec
	v_cvt_pk_bf16_f32 v94, v94, v95
	v_cvt_pk_bf16_f32 v95, v104, v105
	ds_bpermute_b32 v226, v242, v92
	ds_bpermute_b32 v227, v242, v93
	ds_bpermute_b32 v228, v242, v94
	ds_bpermute_b32 v229, v242, v95
	v_pk_mul_f32 v[90:91], v[90:91], v[102:103] op_sel_hi:[1,0]
	v_pk_mul_f32 v[88:89], v[88:89], v[102:103] op_sel_hi:[1,0]
	v_pk_mul_f32 v[92:93], v[86:87], v[102:103] op_sel_hi:[1,0]
	v_pk_mul_f32 v[86:87], v[84:85], v[102:103] op_sel_hi:[1,0]
	v_cvt_pk_bf16_f32 v84, v88, v89
	v_cvt_pk_bf16_f32 v85, v90, v91
	s_nop 0
	v_cvt_pk_bf16_f32 v86, v86, v87
	v_cvt_pk_bf16_f32 v87, v92, v93
	ds_bpermute_b32 v230, v242, v84
	ds_bpermute_b32 v231, v242, v85
	ds_bpermute_b32 v232, v242, v86
	ds_bpermute_b32 v233, v242, v87
	s_waitcnt lgkmcnt(0)
	global_store_dwordx4 v[100:101], v[226:229], off
	global_store_dwordx4 v[100:101], v[230:233], off offset:256
	s_or_b64 exec, exec, s[6:7]
	s_xor_b64 s[42:43], s[70:71], -1
	s_and_saveexec_b64 s[6:7], s[42:43]
	s_cbranch_execnz .LBB0_800
	s_branch .LBB0_801

.LBB0_801:
	s_or_b64 exec, exec, s[6:7]
	s_mov_b64 s[6:7], 0
	s_mov_b64 s[52:53], 0
	s_and_saveexec_b64 s[42:43], s[70:71]
	s_cbranch_execz .LBB0_803
	v_add_f32_e32 v85, v148, v149
	v_add_f32_e32 v86, v150, v151
	v_add_f32_e32 v85, v85, v86
	v_fmamk_f32 v85, v85, 0x3a800000, v241
	v_rsq_f32_e32 v86, v85
	v_add_u32_e32 v84, 48, v244
	v_mad_i64_i32 v[84:85], s[52:53], s26, v84, 0
	v_cndmask_b32_e64 v86, v86, 1.0, s[44:45]
	v_lshl_add_u64 v[84:85], v[84:85], 1, s[34:35]
	v_mul_f32_e32 v86, s38, v86
	v_lshl_add_u64 v[84:85], v[246:247], 1, v[84:85]
	v_pk_mul_f32 v[82:83], v[82:83], v[86:87] op_sel_hi:[1,0]
	v_pk_mul_f32 v[80:81], v[80:81], v[86:87] op_sel_hi:[1,0]
	v_pk_mul_f32 v[88:89], v[78:79], v[86:87] op_sel_hi:[1,0]
	v_pk_mul_f32 v[78:79], v[76:77], v[86:87] op_sel_hi:[1,0]
	v_cvt_pk_bf16_f32 v76, v80, v81
	v_cvt_pk_bf16_f32 v77, v82, v83
	s_and_b64 s[52:53], s[80:81], exec
	v_cvt_pk_bf16_f32 v78, v78, v79
	v_cvt_pk_bf16_f32 v79, v88, v89
	ds_bpermute_b32 v226, v242, v76
	ds_bpermute_b32 v227, v242, v77
	ds_bpermute_b32 v228, v242, v78
	ds_bpermute_b32 v229, v242, v79
	v_pk_mul_f32 v[74:75], v[74:75], v[86:87] op_sel_hi:[1,0]
	v_pk_mul_f32 v[72:73], v[72:73], v[86:87] op_sel_hi:[1,0]
	v_pk_mul_f32 v[76:77], v[70:71], v[86:87] op_sel_hi:[1,0]
	v_pk_mul_f32 v[70:71], v[68:69], v[86:87] op_sel_hi:[1,0]
	v_cvt_pk_bf16_f32 v68, v72, v73
	v_cvt_pk_bf16_f32 v69, v74, v75
	s_nop 0
	v_cvt_pk_bf16_f32 v70, v70, v71
	v_cvt_pk_bf16_f32 v71, v76, v77
	ds_bpermute_b32 v230, v242, v68
	ds_bpermute_b32 v231, v242, v69
	ds_bpermute_b32 v232, v242, v70
	ds_bpermute_b32 v233, v242, v71
	s_waitcnt lgkmcnt(0)
	global_store_dwordx4 v[84:85], v[226:229], off
	global_store_dwordx4 v[84:85], v[230:233], off offset:256
.LBB0_803:
	s_or_b64 exec, exec, s[42:43]
	s_nop 0
	v_add_u32_e32 v68, 0x80, v182
	v_ashrrev_i32_e32 v68, 5, v68
	v_cmp_eq_u32_e32 vcc, s65, v68
	s_or_b64 s[52:53], s[52:53], vcc
	s_and_saveexec_b64 s[42:43], s[52:53]
	s_cbranch_execz .LBB0_814
	v_mov_b32_e32 v68, v145
	v_mov_b32_e32 v69, v146
	v_mov_b32_e32 v145, v147
	v_pk_add_f32 v[68:69], v[68:69], v[144:145]
	v_mad_i64_i32 v[70:71], s[6:7], s26, v245, 0
	v_add_f32_e32 v68, v68, v69
	v_fmamk_f32 v68, v68, 0x3a800000, v241
	v_rsq_f32_e32 v68, v68
	v_lshl_add_u64 v[70:71], v[70:71], 1, s[34:35]
	v_lshl_add_u64 v[70:71], v[246:247], 1, v[70:71]
	s_and_b64 s[6:7], s[80:81], exec
	v_cndmask_b32_e64 v68, v68, 1.0, s[44:45]
	v_mul_f32_e32 v68, s38, v68
	v_pk_mul_f32 v[66:67], v[66:67], v[68:69] op_sel_hi:[1,0]
	v_pk_mul_f32 v[64:65], v[64:65], v[68:69] op_sel_hi:[1,0]
	v_pk_mul_f32 v[72:73], v[62:63], v[68:69] op_sel_hi:[1,0]
	v_pk_mul_f32 v[62:63], v[60:61], v[68:69] op_sel_hi:[1,0]
	v_cvt_pk_bf16_f32 v60, v64, v65
	v_cvt_pk_bf16_f32 v61, v66, v67
	v_pk_mul_f32 v[58:59], v[58:59], v[68:69] op_sel_hi:[1,0]
	v_cvt_pk_bf16_f32 v62, v62, v63
	v_cvt_pk_bf16_f32 v63, v72, v73
	ds_bpermute_b32 v226, v242, v60
	ds_bpermute_b32 v227, v242, v61
	ds_bpermute_b32 v228, v242, v62
	ds_bpermute_b32 v229, v242, v63
	v_pk_mul_f32 v[56:57], v[56:57], v[68:69] op_sel_hi:[1,0]
	s_nop 0
	v_pk_mul_f32 v[60:61], v[54:55], v[68:69] op_sel_hi:[1,0]
	v_pk_mul_f32 v[54:55], v[52:53], v[68:69] op_sel_hi:[1,0]
	v_cvt_pk_bf16_f32 v52, v56, v57
	v_cvt_pk_bf16_f32 v53, v58, v59
	s_nop 0
	v_cvt_pk_bf16_f32 v54, v54, v55
	v_cvt_pk_bf16_f32 v55, v60, v61
	ds_bpermute_b32 v230, v242, v52
	ds_bpermute_b32 v231, v242, v53
	ds_bpermute_b32 v232, v242, v54
	ds_bpermute_b32 v233, v242, v55
	s_waitcnt lgkmcnt(0)
	global_store_dwordx4 v[70:71], v[226:229], off
	global_store_dwordx4 v[70:71], v[230:233], off offset:256
	s_or_b64 exec, exec, s[42:43]
	s_xor_b64 s[52:53], s[6:7], -1
	s_and_saveexec_b64 s[42:43], s[52:53]
	s_cbranch_execnz .LBB0_815

.LBB0_806:
	v_add_f32_e32 v53, v140, v141
	v_add_f32_e32 v54, v142, v143
	v_add_f32_e32 v53, v53, v54
	v_fmamk_f32 v53, v53, 0x3a800000, v241
	v_rsq_f32_e32 v54, v53
	v_add_u32_e32 v52, 0x90, v244
	v_mad_i64_i32 v[52:53], s[6:7], s26, v52, 0
	v_cndmask_b32_e64 v54, v54, 1.0, s[44:45]
	v_lshl_add_u64 v[52:53], v[52:53], 1, s[34:35]
	v_mul_f32_e32 v54, s38, v54
	v_lshl_add_u64 v[52:53], v[246:247], 1, v[52:53]
	v_pk_mul_f32 v[50:51], v[50:51], v[54:55] op_sel_hi:[1,0]
	v_pk_mul_f32 v[48:49], v[48:49], v[54:55] op_sel_hi:[1,0]
	v_pk_mul_f32 v[56:57], v[46:47], v[54:55] op_sel_hi:[1,0]
	v_pk_mul_f32 v[46:47], v[44:45], v[54:55] op_sel_hi:[1,0]
	v_cvt_pk_bf16_f32 v44, v48, v49
	v_cvt_pk_bf16_f32 v45, v50, v51
	s_and_b64 s[52:53], s[80:81], exec
	v_cvt_pk_bf16_f32 v46, v46, v47
	v_cvt_pk_bf16_f32 v47, v56, v57
	ds_bpermute_b32 v226, v242, v44
	ds_bpermute_b32 v227, v242, v45
	ds_bpermute_b32 v228, v242, v46
	ds_bpermute_b32 v229, v242, v47
	v_pk_mul_f32 v[42:43], v[42:43], v[54:55] op_sel_hi:[1,0]
	v_pk_mul_f32 v[40:41], v[40:41], v[54:55] op_sel_hi:[1,0]
	v_pk_mul_f32 v[44:45], v[38:39], v[54:55] op_sel_hi:[1,0]
	v_pk_mul_f32 v[38:39], v[36:37], v[54:55] op_sel_hi:[1,0]
	v_cvt_pk_bf16_f32 v36, v40, v41
	v_cvt_pk_bf16_f32 v37, v42, v43
	s_nop 0
	v_cvt_pk_bf16_f32 v38, v38, v39
	v_cvt_pk_bf16_f32 v39, v44, v45
	ds_bpermute_b32 v230, v242, v36
	ds_bpermute_b32 v231, v242, v37
	ds_bpermute_b32 v232, v242, v38
	ds_bpermute_b32 v233, v242, v39
	s_waitcnt lgkmcnt(0)
	global_store_dwordx4 v[52:53], v[226:229], off
	global_store_dwordx4 v[52:53], v[230:233], off offset:256
	s_or_b64 exec, exec, s[42:43]
	s_xor_b64 s[42:43], s[52:53], -1
	s_and_saveexec_b64 s[6:7], s[42:43]
	s_cbranch_execnz .LBB0_817

.LBB0_808:
	v_add_f32_e32 v37, v136, v137
	v_add_f32_e32 v38, v138, v139
	v_add_f32_e32 v37, v37, v38
	v_fmamk_f32 v37, v37, 0x3a800000, v241
	v_rsq_f32_e32 v38, v37
	v_add_u32_e32 v36, 0xa0, v244
	v_mad_i64_i32 v[36:37], s[42:43], s26, v36, 0
	v_cndmask_b32_e64 v38, v38, 1.0, s[44:45]
	v_lshl_add_u64 v[36:37], v[36:37], 1, s[34:35]
	v_mul_f32_e32 v38, s38, v38
	v_lshl_add_u64 v[36:37], v[246:247], 1, v[36:37]
	v_pk_mul_f32 v[34:35], v[34:35], v[38:39] op_sel_hi:[1,0]
	v_pk_mul_f32 v[32:33], v[32:33], v[38:39] op_sel_hi:[1,0]
	v_pk_mul_f32 v[40:41], v[30:31], v[38:39] op_sel_hi:[1,0]
	v_pk_mul_f32 v[30:31], v[28:29], v[38:39] op_sel_hi:[1,0]
	v_cvt_pk_bf16_f32 v28, v32, v33
	v_cvt_pk_bf16_f32 v29, v34, v35
	s_and_b64 s[42:43], s[80:81], exec
	v_cvt_pk_bf16_f32 v30, v30, v31
	v_cvt_pk_bf16_f32 v31, v40, v41
	ds_bpermute_b32 v226, v242, v28
	ds_bpermute_b32 v227, v242, v29
	ds_bpermute_b32 v228, v242, v30
	ds_bpermute_b32 v229, v242, v31
	v_pk_mul_f32 v[26:27], v[26:27], v[38:39] op_sel_hi:[1,0]
	v_pk_mul_f32 v[24:25], v[24:25], v[38:39] op_sel_hi:[1,0]
	v_pk_mul_f32 v[28:29], v[22:23], v[38:39] op_sel_hi:[1,0]
	v_pk_mul_f32 v[22:23], v[20:21], v[38:39] op_sel_hi:[1,0]
	v_cvt_pk_bf16_f32 v20, v24, v25
	v_cvt_pk_bf16_f32 v21, v26, v27
	s_nop 0
	v_cvt_pk_bf16_f32 v22, v22, v23
	v_cvt_pk_bf16_f32 v23, v28, v29
	ds_bpermute_b32 v230, v242, v20
	ds_bpermute_b32 v231, v242, v21
	ds_bpermute_b32 v232, v242, v22
	ds_bpermute_b32 v233, v242, v23
	s_waitcnt lgkmcnt(0)
	global_store_dwordx4 v[36:37], v[226:229], off
	global_store_dwordx4 v[36:37], v[230:233], off offset:256
.LBB0_809:
	s_or_b64 exec, exec, s[6:7]
	s_nop 0
	v_add_u32_e32 v20, 0xb0, v182
	v_ashrrev_i32_e32 v20, 5, v20
	v_cmp_eq_u32_e32 vcc, s65, v20
	s_or_b64 s[42:43], s[42:43], vcc
	s_and_saveexec_b64 s[6:7], s[42:43]
	s_cbranch_execz .LBB0_811
	v_add_f32_e32 v21, v132, v133
	v_add_f32_e32 v22, v134, v135
	v_add_f32_e32 v21, v21, v22
	v_fmamk_f32 v21, v21, 0x3a800000, v241
	v_rsq_f32_e32 v22, v21
	v_add_u32_e32 v20, 0xb0, v244
	v_mad_i64_i32 v[20:21], s[42:43], s26, v20, 0
	v_cndmask_b32_e64 v22, v22, 1.0, s[44:45]
	v_lshl_add_u64 v[20:21], v[20:21], 1, s[34:35]
	v_mul_f32_e32 v22, s38, v22
	v_lshl_add_u64 v[20:21], v[246:247], 1, v[20:21]
	v_pk_mul_f32 v[18:19], v[18:19], v[22:23] op_sel_hi:[1,0]
	v_pk_mul_f32 v[16:17], v[16:17], v[22:23] op_sel_hi:[1,0]
	v_pk_mul_f32 v[24:25], v[14:15], v[22:23] op_sel_hi:[1,0]
	v_pk_mul_f32 v[14:15], v[12:13], v[22:23] op_sel_hi:[1,0]
	v_cvt_pk_bf16_f32 v12, v16, v17
	v_cvt_pk_bf16_f32 v13, v18, v19
	v_pk_mul_f32 v[10:11], v[10:11], v[22:23] op_sel_hi:[1,0]
	v_cvt_pk_bf16_f32 v14, v14, v15
	v_cvt_pk_bf16_f32 v15, v24, v25
	ds_bpermute_b32 v226, v242, v12
	ds_bpermute_b32 v227, v242, v13
	ds_bpermute_b32 v228, v242, v14
	ds_bpermute_b32 v229, v242, v15
	v_pk_mul_f32 v[8:9], v[8:9], v[22:23] op_sel_hi:[1,0]
	s_nop 0
	v_pk_mul_f32 v[12:13], v[6:7], v[22:23] op_sel_hi:[1,0]
	v_pk_mul_f32 v[6:7], v[4:5], v[22:23] op_sel_hi:[1,0]
	v_cvt_pk_bf16_f32 v4, v8, v9
	v_cvt_pk_bf16_f32 v5, v10, v11
	s_nop 0
	v_cvt_pk_bf16_f32 v6, v6, v7
	v_cvt_pk_bf16_f32 v7, v12, v13
	ds_bpermute_b32 v230, v242, v4
	ds_bpermute_b32 v231, v242, v5
	ds_bpermute_b32 v232, v242, v6
	ds_bpermute_b32 v233, v242, v7
	s_waitcnt lgkmcnt(0)
	global_store_dwordx4 v[20:21], v[226:229], off
	global_store_dwordx4 v[20:21], v[230:233], off offset:256
